# EpiRes epilogues: counted vmcnt on fused-norm path (residual loads no longer wait for previous group's store acks)
# baseline (speedup 1.0000x reference)
.LBB0_199:
	s_andn2_b64 vcc, exec, s[36:37]
	s_cbranch_vccnz .LBB0_201
	global_store_dwordx4 v[212:213], v[166:169], off offset:64
	global_store_dwordx4 v[212:213], v[170:173], off offset:512
	global_store_dwordx4 v[212:213], v[174:177], off offset:576
	s_waitcnt vmcnt(5)
.LBB0_201:
	v_lshlrev_b64 v[166:167], 10, v[210:211]
	v_lshl_add_u64 v[168:169], v[166:167], 0, v[190:191]
	v_or_b32_e32 v166, 48, v208
	v_ashrrev_i32_e32 v167, 31, v166
	s_waitcnt vmcnt(12)
	v_pk_fma_f32 v[150:151], v[118:119], v[54:55], v[150:151]
	v_lshlrev_b64 v[118:119], 12, v[166:167]
	v_lshl_add_u64 v[118:119], s[16:17], 0, v[118:119]
	v_lshl_add_u64 v[118:119], v[190:191], 2, v[118:119]
	v_pk_fma_f32 v[164:165], v[132:133], v[72:73], v[164:165]
	v_pk_fma_f32 v[162:163], v[130:131], v[70:71], v[162:163]
	v_pk_fma_f32 v[160:161], v[128:129], v[64:65], v[160:161]
	v_pk_fma_f32 v[158:159], v[126:127], v[62:63], v[158:159]
	v_pk_fma_f32 v[156:157], v[124:125], v[60:61], v[156:157]
	v_pk_fma_f32 v[154:155], v[122:123], v[58:59], v[154:155]
	v_pk_fma_f32 v[152:153], v[120:121], v[56:57], v[152:153]
	global_load_dwordx4 v[130:133], v[118:119], off
	global_load_dwordx4 v[126:129], v[118:119], off offset:64
	global_load_dwordx4 v[122:125], v[118:119], off offset:512
	s_nop 0
	global_load_dwordx4 v[118:121], v[118:119], off offset:576
	v_lshl_add_u64 v[170:171], v[168:169], 2, s[90:91]
	s_mov_b64 s[36:37], -1
	s_and_b64 vcc, exec, s[8:9]
	global_store_dwordx4 v[170:171], v[162:165], off
	s_cbranch_vccnz .LBB0_205
	v_mul_f32_e32 v172, v163, v163
	v_mul_f32_e32 v173, v165, v165
	v_fmac_f32_e32 v172, v162, v162
	v_fmac_f32_e32 v173, v164, v164
	v_pk_mul_f32 v[164:165], v[200:201], v[164:165]
	v_pk_mul_f32 v[162:163], v[202:203], v[162:163]
	v_add_f32_e32 v172, v172, v173
	v_cvt_pk_bf16_f32 v162, v162, v163
	v_cvt_pk_bf16_f32 v163, v164, v165
	v_lshl_add_u64 v[164:165], v[168:169], 1, s[96:97]
	global_store_dwordx2 v[164:165], v[162:163], off
	global_store_dwordx4 v[170:171], v[158:161], off offset:64
	v_mul_f32_e32 v162, v159, v159
	v_mul_f32_e32 v163, v161, v161
	v_fmac_f32_e32 v162, v158, v158
	v_fmac_f32_e32 v163, v160, v160
	v_add_f32_e32 v162, v162, v163
	v_pk_mul_f32 v[168:169], v[198:199], v[158:159]
	v_add_f32_e32 v172, v172, v162
	v_pk_mul_f32 v[162:163], v[196:197], v[160:161]
	v_cvt_pk_bf16_f32 v168, v168, v169
	v_mul_f32_e32 v173, v153, v153
	v_cvt_pk_bf16_f32 v169, v162, v163
	global_store_dwordx2 v[164:165], v[168:169], off offset:32
	global_store_dwordx4 v[170:171], v[154:157], off offset:512
	v_mul_f32_e32 v162, v155, v155
	v_mul_f32_e32 v163, v157, v157
	v_pk_mul_f32 v[168:169], v[194:195], v[154:155]
	v_fmac_f32_e32 v162, v154, v154
	v_fmac_f32_e32 v163, v156, v156
	v_cvt_pk_bf16_f32 v168, v168, v169
	v_mul_f32_e32 v169, v151, v151
	v_add_f32_e32 v162, v162, v163
	v_fmac_f32_e32 v169, v150, v150
	v_fmac_f32_e32 v173, v152, v152
	v_add_f32_e32 v172, v162, v172
	v_add_f32_e32 v169, v169, v173
	v_add_f32_e32 v172, v169, v172
	ds_bpermute_b32 v173, v226, v172
	v_pk_mul_f32 v[162:163], v[192:193], v[156:157]
	s_nop 0
	v_cvt_pk_bf16_f32 v169, v162, v163
	global_store_dwordx2 v[164:165], v[168:169], off offset:256
	global_store_dwordx4 v[170:171], v[150:153], off offset:576
	s_waitcnt lgkmcnt(0)
	v_add_f32_e32 v162, v172, v173
	ds_bpermute_b32 v163, v225, v162
	v_pk_mul_f32 v[172:173], v[186:187], v[150:151]
	v_pk_mul_f32 v[168:169], v[188:189], v[152:153]
	v_cvt_pk_bf16_f32 v172, v172, v173
	s_nop 0
	v_cvt_pk_bf16_f32 v173, v168, v169
	global_store_dwordx2 v[164:165], v[172:173], off offset:288
	s_and_saveexec_b64 s[36:37], s[6:7]
	s_cbranch_execz .LBB0_204
	s_waitcnt lgkmcnt(0)
	v_add_f32_e32 v162, v162, v163
	v_fma_f32 v162, v162, s78, 0.5
	v_trunc_f32_e32 v162, v162
	v_mul_f32_e32 v163, 0x2f800000, v162
	v_floor_f32_e32 v163, v163
	v_fmac_f32_e32 v162, 0xcf800000, v163
	v_cvt_u32_f32_e32 v162, v162
	v_cvt_u32_f32_e32 v163, v163
	v_lshl_add_u64 v[164:165], v[210:211], 3, s[14:15]
	global_atomic_add_x2 v[164:165], v[162:163], off

.LBB0_205:
	s_andn2_b64 vcc, exec, s[36:37]
	s_cbranch_vccnz .LBB0_207
	global_store_dwordx4 v[170:171], v[158:161], off offset:64
	global_store_dwordx4 v[170:171], v[154:157], off offset:512
	global_store_dwordx4 v[170:171], v[150:153], off offset:576
	s_waitcnt vmcnt(6)
.LBB0_207:
	s_nop 1
	v_lshlrev_b64 v[150:151], 10, v[206:207]
	v_lshl_add_u64 v[152:153], v[150:151], 0, v[190:191]
	v_add_u32_e32 v150, 0x80, v208
	v_ashrrev_i32_e32 v151, 31, v150
	s_waitcnt vmcnt(20)
	v_pk_fma_f32 v[134:135], v[102:103], v[54:55], v[134:135]
	v_lshlrev_b64 v[102:103], 12, v[150:151]
	v_lshl_add_u64 v[102:103], s[16:17], 0, v[102:103]
	v_lshl_add_u64 v[102:103], v[190:191], 2, v[102:103]
	v_pk_fma_f32 v[148:149], v[116:117], v[72:73], v[148:149]
	v_pk_fma_f32 v[146:147], v[114:115], v[70:71], v[146:147]
	v_pk_fma_f32 v[144:145], v[112:113], v[64:65], v[144:145]
	v_pk_fma_f32 v[142:143], v[110:111], v[62:63], v[142:143]
	v_pk_fma_f32 v[140:141], v[108:109], v[60:61], v[140:141]
	v_pk_fma_f32 v[138:139], v[106:107], v[58:59], v[138:139]
	v_pk_fma_f32 v[136:137], v[104:105], v[56:57], v[136:137]
	global_load_dwordx4 v[114:117], v[102:103], off
	global_load_dwordx4 v[110:113], v[102:103], off offset:64
	global_load_dwordx4 v[106:109], v[102:103], off offset:512
	s_nop 0
	global_load_dwordx4 v[102:105], v[102:103], off offset:576
	v_lshl_add_u64 v[154:155], v[152:153], 2, s[90:91]
	s_mov_b64 s[36:37], -1
	s_and_b64 vcc, exec, s[8:9]
	global_store_dwordx4 v[154:155], v[146:149], off
	s_cbranch_vccnz .LBB0_211
	v_mul_f32_e32 v156, v147, v147
	v_mul_f32_e32 v157, v149, v149
	v_fmac_f32_e32 v156, v146, v146
	v_fmac_f32_e32 v157, v148, v148
	v_pk_mul_f32 v[148:149], v[200:201], v[148:149]
	v_pk_mul_f32 v[146:147], v[202:203], v[146:147]
	v_add_f32_e32 v156, v156, v157
	v_cvt_pk_bf16_f32 v146, v146, v147
	v_cvt_pk_bf16_f32 v147, v148, v149
	v_lshl_add_u64 v[148:149], v[152:153], 1, s[96:97]
	global_store_dwordx2 v[148:149], v[146:147], off
	global_store_dwordx4 v[154:155], v[142:145], off offset:64
	v_mul_f32_e32 v146, v143, v143
	v_mul_f32_e32 v147, v145, v145
	v_fmac_f32_e32 v146, v142, v142
	v_fmac_f32_e32 v147, v144, v144
	v_add_f32_e32 v146, v146, v147
	v_pk_mul_f32 v[152:153], v[198:199], v[142:143]
	v_add_f32_e32 v156, v156, v146
	v_pk_mul_f32 v[146:147], v[196:197], v[144:145]
	v_cvt_pk_bf16_f32 v152, v152, v153
	v_mul_f32_e32 v157, v137, v137
	v_cvt_pk_bf16_f32 v153, v146, v147
	global_store_dwordx2 v[148:149], v[152:153], off offset:32
	global_store_dwordx4 v[154:155], v[138:141], off offset:512
	v_mul_f32_e32 v146, v139, v139
	v_mul_f32_e32 v147, v141, v141
	v_pk_mul_f32 v[152:153], v[194:195], v[138:139]
	v_fmac_f32_e32 v146, v138, v138
	v_fmac_f32_e32 v147, v140, v140
	v_cvt_pk_bf16_f32 v152, v152, v153
	v_mul_f32_e32 v153, v135, v135
	v_add_f32_e32 v146, v146, v147
	v_fmac_f32_e32 v153, v134, v134
	v_fmac_f32_e32 v157, v136, v136
	v_add_f32_e32 v156, v146, v156
	v_add_f32_e32 v153, v153, v157
	v_add_f32_e32 v156, v153, v156
	ds_bpermute_b32 v157, v226, v156
	v_pk_mul_f32 v[146:147], v[192:193], v[140:141]
	s_nop 0
	v_cvt_pk_bf16_f32 v153, v146, v147
	global_store_dwordx2 v[148:149], v[152:153], off offset:256
	global_store_dwordx4 v[154:155], v[134:137], off offset:576
	s_waitcnt lgkmcnt(0)
	v_add_f32_e32 v146, v156, v157
	ds_bpermute_b32 v147, v225, v146
	v_pk_mul_f32 v[156:157], v[186:187], v[134:135]
	v_pk_mul_f32 v[152:153], v[188:189], v[136:137]
	v_cvt_pk_bf16_f32 v156, v156, v157
	s_nop 0
	v_cvt_pk_bf16_f32 v157, v152, v153
	global_store_dwordx2 v[148:149], v[156:157], off offset:288
	s_and_saveexec_b64 s[36:37], s[6:7]
	s_cbranch_execz .LBB0_210
	s_waitcnt lgkmcnt(0)
	v_add_f32_e32 v146, v146, v147
	v_fma_f32 v146, v146, s78, 0.5
	v_trunc_f32_e32 v146, v146
	v_mul_f32_e32 v147, 0x2f800000, v146
	v_floor_f32_e32 v147, v147
	v_fmac_f32_e32 v146, 0xcf800000, v147
	v_cvt_u32_f32_e32 v146, v146
	v_cvt_u32_f32_e32 v147, v147
	v_lshl_add_u64 v[148:149], v[206:207], 3, s[14:15]
	global_atomic_add_x2 v[148:149], v[146:147], off

.LBB0_211:
	s_andn2_b64 vcc, exec, s[36:37]
	s_cbranch_vccnz .LBB0_213
	global_store_dwordx4 v[154:155], v[142:145], off offset:64
	global_store_dwordx4 v[154:155], v[138:141], off offset:512
	global_store_dwordx4 v[154:155], v[134:137], off offset:576
	s_waitcnt vmcnt(6)
.LBB0_213:
	s_waitcnt vmcnt(20)
	v_pk_fma_f32 v[118:119], v[86:87], v[54:55], v[118:119]
	v_lshl_add_u64 v[86:87], s[16:17], 0, v[204:205]
	v_lshl_add_u64 v[86:87], v[190:191], 2, v[86:87]
	s_mov_b64 s[2:3], 0x90000
	v_pk_fma_f32 v[130:131], v[98:99], v[70:71], v[130:131]
	v_lshl_add_u64 v[98:99], v[86:87], 0, s[2:3]
	v_add_co_u32_e32 v86, vcc, 0x90000, v86
	v_pk_fma_f32 v[132:133], v[100:101], v[72:73], v[132:133]
	s_nop 0
	v_addc_co_u32_e32 v87, vcc, 0, v87, vcc
	v_pk_fma_f32 v[128:129], v[96:97], v[64:65], v[128:129]
	v_pk_fma_f32 v[126:127], v[94:95], v[62:63], v[126:127]
	v_pk_fma_f32 v[124:125], v[92:93], v[60:61], v[124:125]
	v_pk_fma_f32 v[122:123], v[90:91], v[58:59], v[122:123]
	v_pk_fma_f32 v[120:121], v[88:89], v[56:57], v[120:121]
	global_load_dwordx4 v[86:89], v[86:87], off
	s_nop 0
	global_load_dwordx4 v[94:97], v[98:99], off offset:64
	global_load_dwordx4 v[90:93], v[98:99], off offset:512
	s_nop 0
	global_load_dwordx4 v[98:101], v[98:99], off offset:576
	v_lshlrev_b64 v[134:135], 10, v[166:167]
	v_lshl_add_u64 v[134:135], v[134:135], 0, v[190:191]
	v_lshl_add_u64 v[136:137], v[134:135], 2, s[90:91]
	s_mov_b64 s[36:37], -1
	s_and_b64 vcc, exec, s[8:9]
	global_store_dwordx4 v[136:137], v[130:133], off
	s_cbranch_vccnz .LBB0_217
	v_mul_f32_e32 v138, v131, v131
	v_mul_f32_e32 v139, v133, v133
	v_fmac_f32_e32 v138, v130, v130
	v_fmac_f32_e32 v139, v132, v132
	v_pk_mul_f32 v[132:133], v[200:201], v[132:133]
	v_pk_mul_f32 v[130:131], v[202:203], v[130:131]
	v_add_f32_e32 v138, v138, v139
	v_cvt_pk_bf16_f32 v130, v130, v131
	v_cvt_pk_bf16_f32 v131, v132, v133
	v_lshl_add_u64 v[132:133], v[134:135], 1, s[96:97]
	global_store_dwordx2 v[132:133], v[130:131], off
	global_store_dwordx4 v[136:137], v[126:129], off offset:64
	v_mul_f32_e32 v130, v127, v127
	v_mul_f32_e32 v131, v129, v129
	v_fmac_f32_e32 v130, v126, v126
	v_fmac_f32_e32 v131, v128, v128
	v_add_f32_e32 v130, v130, v131
	v_pk_mul_f32 v[134:135], v[198:199], v[126:127]
	v_add_f32_e32 v138, v138, v130
	v_pk_mul_f32 v[130:131], v[196:197], v[128:129]
	v_cvt_pk_bf16_f32 v134, v134, v135
	v_mul_f32_e32 v139, v121, v121
	v_cvt_pk_bf16_f32 v135, v130, v131
	global_store_dwordx2 v[132:133], v[134:135], off offset:32
	global_store_dwordx4 v[136:137], v[122:125], off offset:512
	v_mul_f32_e32 v130, v123, v123
	v_mul_f32_e32 v131, v125, v125
	v_pk_mul_f32 v[134:135], v[194:195], v[122:123]
	v_fmac_f32_e32 v130, v122, v122
	v_fmac_f32_e32 v131, v124, v124
	v_cvt_pk_bf16_f32 v134, v134, v135
	v_mul_f32_e32 v135, v119, v119
	v_add_f32_e32 v130, v130, v131
	v_fmac_f32_e32 v135, v118, v118
	v_fmac_f32_e32 v139, v120, v120
	v_add_f32_e32 v138, v130, v138
	v_add_f32_e32 v135, v135, v139
	v_add_f32_e32 v138, v135, v138
	ds_bpermute_b32 v139, v226, v138
	v_pk_mul_f32 v[130:131], v[192:193], v[124:125]
	s_nop 0
	v_cvt_pk_bf16_f32 v135, v130, v131
	global_store_dwordx2 v[132:133], v[134:135], off offset:256
	global_store_dwordx4 v[136:137], v[118:121], off offset:576
	s_waitcnt lgkmcnt(0)
	v_add_f32_e32 v130, v138, v139
	ds_bpermute_b32 v131, v225, v130
	v_pk_mul_f32 v[138:139], v[186:187], v[118:119]
	v_pk_mul_f32 v[134:135], v[188:189], v[120:121]
	v_cvt_pk_bf16_f32 v138, v138, v139
	s_nop 0
	v_cvt_pk_bf16_f32 v139, v134, v135
	global_store_dwordx2 v[132:133], v[138:139], off offset:288
	s_and_saveexec_b64 s[36:37], s[6:7]
	s_cbranch_execz .LBB0_216
	s_waitcnt lgkmcnt(0)
	v_add_f32_e32 v130, v130, v131
	v_fma_f32 v130, v130, s78, 0.5
	v_trunc_f32_e32 v130, v130
	v_mul_f32_e32 v131, 0x2f800000, v130
	v_floor_f32_e32 v131, v131
	v_fmac_f32_e32 v130, 0xcf800000, v131
	v_cvt_u32_f32_e32 v130, v130
	v_cvt_u32_f32_e32 v131, v131
	v_lshl_add_u64 v[132:133], v[166:167], 3, s[14:15]
	global_atomic_add_x2 v[132:133], v[130:131], off

.LBB0_217:
	s_andn2_b64 vcc, exec, s[36:37]
	s_cbranch_vccnz .LBB0_219
	global_store_dwordx4 v[136:137], v[126:129], off offset:64
	global_store_dwordx4 v[136:137], v[122:125], off offset:512
	global_store_dwordx4 v[136:137], v[118:121], off offset:576
	s_waitcnt vmcnt(6)
.LBB0_219:
	s_nop 1
	v_lshlrev_b64 v[118:119], 10, v[150:151]
	v_lshl_add_u64 v[120:121], v[118:119], 0, v[190:191]
	v_or_b32_e32 v118, 32, v150
	v_ashrrev_i32_e32 v119, 31, v118
	s_waitcnt vmcnt(20)
	v_pk_fma_f32 v[102:103], v[66:67], v[54:55], v[102:103]
	v_lshlrev_b64 v[66:67], 12, v[118:119]
	v_lshl_add_u64 v[66:67], s[16:17], 0, v[66:67]
	v_lshl_add_u64 v[66:67], v[190:191], 2, v[66:67]
	v_pk_fma_f32 v[116:117], v[84:85], v[72:73], v[116:117]
	v_pk_fma_f32 v[114:115], v[82:83], v[70:71], v[114:115]
	v_pk_fma_f32 v[112:113], v[80:81], v[64:65], v[112:113]
	v_pk_fma_f32 v[110:111], v[78:79], v[62:63], v[110:111]
	v_pk_fma_f32 v[108:109], v[76:77], v[60:61], v[108:109]
	v_pk_fma_f32 v[106:107], v[74:75], v[58:59], v[106:107]
	v_pk_fma_f32 v[104:105], v[68:69], v[56:57], v[104:105]
	global_load_dwordx4 v[82:85], v[66:67], off
	global_load_dwordx4 v[78:81], v[66:67], off offset:64
	global_load_dwordx4 v[74:77], v[66:67], off offset:512
	s_nop 0
	global_load_dwordx4 v[66:69], v[66:67], off offset:576
	v_lshl_add_u64 v[122:123], v[120:121], 2, s[90:91]
	s_mov_b64 s[36:37], -1
	s_and_b64 vcc, exec, s[8:9]
	global_store_dwordx4 v[122:123], v[114:117], off
	s_cbranch_vccnz .LBB0_223
	v_mul_f32_e32 v124, v115, v115
	v_mul_f32_e32 v125, v117, v117
	v_fmac_f32_e32 v124, v114, v114
	v_fmac_f32_e32 v125, v116, v116
	v_pk_mul_f32 v[116:117], v[200:201], v[116:117]
	v_pk_mul_f32 v[114:115], v[202:203], v[114:115]
	v_add_f32_e32 v124, v124, v125
	v_cvt_pk_bf16_f32 v114, v114, v115
	v_cvt_pk_bf16_f32 v115, v116, v117
	v_lshl_add_u64 v[116:117], v[120:121], 1, s[96:97]
	global_store_dwordx2 v[116:117], v[114:115], off
	global_store_dwordx4 v[122:123], v[110:113], off offset:64
	v_mul_f32_e32 v114, v111, v111
	v_mul_f32_e32 v115, v113, v113
	v_fmac_f32_e32 v114, v110, v110
	v_fmac_f32_e32 v115, v112, v112
	v_add_f32_e32 v114, v114, v115
	v_pk_mul_f32 v[120:121], v[198:199], v[110:111]
	v_add_f32_e32 v124, v124, v114
	v_pk_mul_f32 v[114:115], v[196:197], v[112:113]
	v_cvt_pk_bf16_f32 v120, v120, v121
	v_mul_f32_e32 v125, v105, v105
	v_cvt_pk_bf16_f32 v121, v114, v115
	global_store_dwordx2 v[116:117], v[120:121], off offset:32
	global_store_dwordx4 v[122:123], v[106:109], off offset:512
	v_mul_f32_e32 v114, v107, v107
	v_mul_f32_e32 v115, v109, v109
	v_pk_mul_f32 v[120:121], v[194:195], v[106:107]
	v_fmac_f32_e32 v114, v106, v106
	v_fmac_f32_e32 v115, v108, v108
	v_cvt_pk_bf16_f32 v120, v120, v121
	v_mul_f32_e32 v121, v103, v103
	v_add_f32_e32 v114, v114, v115
	v_fmac_f32_e32 v121, v102, v102
	v_fmac_f32_e32 v125, v104, v104
	v_add_f32_e32 v124, v114, v124
	v_add_f32_e32 v121, v121, v125
	v_add_f32_e32 v124, v121, v124
	ds_bpermute_b32 v125, v226, v124
	v_pk_mul_f32 v[114:115], v[192:193], v[108:109]
	s_nop 0
	v_cvt_pk_bf16_f32 v121, v114, v115
	global_store_dwordx2 v[116:117], v[120:121], off offset:256
	global_store_dwordx4 v[122:123], v[102:105], off offset:576
	s_waitcnt lgkmcnt(0)
	v_add_f32_e32 v114, v124, v125
	ds_bpermute_b32 v115, v225, v114
	v_pk_mul_f32 v[124:125], v[186:187], v[102:103]
	v_pk_mul_f32 v[120:121], v[188:189], v[104:105]
	v_cvt_pk_bf16_f32 v124, v124, v125
	s_nop 0
	v_cvt_pk_bf16_f32 v125, v120, v121
	global_store_dwordx2 v[116:117], v[124:125], off offset:288
	s_and_saveexec_b64 s[36:37], s[6:7]
	s_cbranch_execz .LBB0_222
	s_waitcnt lgkmcnt(0)
	v_add_f32_e32 v114, v114, v115
	v_fma_f32 v114, v114, s78, 0.5
	v_trunc_f32_e32 v114, v114
	v_mul_f32_e32 v115, 0x2f800000, v114
	v_floor_f32_e32 v115, v115
	v_fmac_f32_e32 v114, 0xcf800000, v115
	v_cvt_u32_f32_e32 v114, v114
	v_cvt_u32_f32_e32 v115, v115
	v_lshl_add_u64 v[116:117], v[150:151], 3, s[14:15]
	global_atomic_add_x2 v[116:117], v[114:115], off

.LBB0_223:
	s_andn2_b64 vcc, exec, s[36:37]
	s_cbranch_vccnz .LBB0_225
	global_store_dwordx4 v[122:123], v[110:113], off offset:64
	global_store_dwordx4 v[122:123], v[106:109], off offset:512
	global_store_dwordx4 v[122:123], v[102:105], off offset:576
	s_waitcnt vmcnt(6)
.LBB0_225:
	s_waitcnt vmcnt(23)
	s_nop 0
	v_pk_fma_f32 v[102:103], v[50:51], v[70:71], v[86:87]
	s_waitcnt vmcnt(22)
	v_pk_fma_f32 v[86:87], v[46:47], v[62:63], v[94:95]
	s_waitcnt vmcnt(20)
	v_pk_fma_f32 v[94:95], v[38:39], v[54:55], v[98:99]
	v_or_b32_e32 v98, 48, v150
	v_ashrrev_i32_e32 v99, 31, v98
	v_lshlrev_b64 v[38:39], 12, v[98:99]
	v_lshl_add_u64 v[38:39], s[16:17], 0, v[38:39]
	v_lshl_add_u64 v[38:39], v[190:191], 2, v[38:39]
	v_pk_fma_f32 v[104:105], v[52:53], v[72:73], v[88:89]
	v_pk_fma_f32 v[88:89], v[48:49], v[64:65], v[96:97]
	v_pk_fma_f32 v[92:93], v[44:45], v[60:61], v[92:93]
	v_pk_fma_f32 v[90:91], v[42:43], v[58:59], v[90:91]
	v_pk_fma_f32 v[96:97], v[40:41], v[56:57], v[100:101]
	global_load_dwordx4 v[50:53], v[38:39], off
	global_load_dwordx4 v[46:49], v[38:39], off offset:64
	global_load_dwordx4 v[42:45], v[38:39], off offset:512
	s_nop 0
	global_load_dwordx4 v[38:41], v[38:39], off offset:576
	v_or_b32_e32 v106, 16, v150
	v_ashrrev_i32_e32 v107, 31, v106
	v_lshlrev_b64 v[108:109], 10, v[106:107]
	v_lshl_add_u64 v[100:101], v[108:109], 0, v[190:191]
	v_lshl_add_u64 v[108:109], v[100:101], 2, s[90:91]
	s_mov_b64 s[36:37], -1
	s_and_b64 vcc, exec, s[8:9]
	global_store_dwordx4 v[108:109], v[102:105], off
	s_cbranch_vccnz .LBB0_229
	v_mul_f32_e32 v110, v103, v103
	v_mul_f32_e32 v111, v105, v105
	v_fmac_f32_e32 v110, v102, v102
	v_fmac_f32_e32 v111, v104, v104
	v_pk_mul_f32 v[104:105], v[200:201], v[104:105]
	v_pk_mul_f32 v[102:103], v[202:203], v[102:103]
	v_add_f32_e32 v110, v110, v111
	v_cvt_pk_bf16_f32 v102, v102, v103
	v_cvt_pk_bf16_f32 v103, v104, v105
	v_lshl_add_u64 v[104:105], v[100:101], 1, s[96:97]
	v_mul_f32_e32 v100, v87, v87
	v_mul_f32_e32 v101, v89, v89
	v_fmac_f32_e32 v100, v86, v86
	v_fmac_f32_e32 v101, v88, v88
	global_store_dwordx2 v[104:105], v[102:103], off
	global_store_dwordx4 v[108:109], v[86:89], off offset:64
	v_add_f32_e32 v100, v100, v101
	v_pk_mul_f32 v[102:103], v[198:199], v[86:87]
	v_add_f32_e32 v110, v110, v100
	v_pk_mul_f32 v[100:101], v[196:197], v[88:89]
	v_cvt_pk_bf16_f32 v102, v102, v103
	v_mul_f32_e32 v111, v97, v97
	v_cvt_pk_bf16_f32 v103, v100, v101
	global_store_dwordx2 v[104:105], v[102:103], off offset:32
	global_store_dwordx4 v[108:109], v[90:93], off offset:512
	v_mul_f32_e32 v100, v91, v91
	v_mul_f32_e32 v101, v93, v93
	v_pk_mul_f32 v[102:103], v[194:195], v[90:91]
	v_fmac_f32_e32 v100, v90, v90
	v_fmac_f32_e32 v101, v92, v92
	v_cvt_pk_bf16_f32 v102, v102, v103
	v_mul_f32_e32 v103, v95, v95
	v_add_f32_e32 v100, v100, v101
	v_fmac_f32_e32 v103, v94, v94
	v_fmac_f32_e32 v111, v96, v96
	v_add_f32_e32 v110, v100, v110
	v_add_f32_e32 v103, v103, v111
	v_add_f32_e32 v110, v103, v110
	ds_bpermute_b32 v111, v226, v110
	v_pk_mul_f32 v[100:101], v[192:193], v[92:93]
	s_nop 0
	v_cvt_pk_bf16_f32 v103, v100, v101
	global_store_dwordx2 v[104:105], v[102:103], off offset:256
	global_store_dwordx4 v[108:109], v[94:97], off offset:576
	s_waitcnt lgkmcnt(0)
	v_add_f32_e32 v100, v110, v111
	ds_bpermute_b32 v101, v225, v100
	v_pk_mul_f32 v[110:111], v[186:187], v[94:95]
	v_pk_mul_f32 v[102:103], v[188:189], v[96:97]
	v_cvt_pk_bf16_f32 v110, v110, v111
	s_nop 0
	v_cvt_pk_bf16_f32 v111, v102, v103
	global_store_dwordx2 v[104:105], v[110:111], off offset:288
	s_and_saveexec_b64 s[36:37], s[6:7]
	s_cbranch_execz .LBB0_228
	s_waitcnt lgkmcnt(0)
	v_add_f32_e32 v100, v100, v101
	v_fma_f32 v100, v100, s78, 0.5
	v_trunc_f32_e32 v100, v100
	v_mul_f32_e32 v101, 0x2f800000, v100
	v_floor_f32_e32 v101, v101
	v_fmac_f32_e32 v100, 0xcf800000, v101
	v_cvt_u32_f32_e32 v100, v100
	v_cvt_u32_f32_e32 v101, v101
	v_lshl_add_u64 v[102:103], v[106:107], 3, s[14:15]
	global_atomic_add_x2 v[102:103], v[100:101], off

.LBB0_229:
	s_andn2_b64 vcc, exec, s[36:37]
	s_cbranch_vccnz .LBB0_231
	global_store_dwordx4 v[108:109], v[86:89], off offset:64
	global_store_dwordx4 v[108:109], v[90:93], off offset:512
	global_store_dwordx4 v[108:109], v[94:97], off offset:576
	s_waitcnt vmcnt(6)
.LBB0_231:
	v_lshlrev_b64 v[86:87], 10, v[118:119]
	s_waitcnt vmcnt(20)
	v_pk_fma_f32 v[24:25], v[24:25], v[56:57], v[68:69]
	v_lshl_add_u64 v[68:69], v[86:87], 0, v[190:191]
	v_pk_fma_f32 v[36:37], v[36:37], v[72:73], v[84:85]
	v_pk_fma_f32 v[34:35], v[34:35], v[70:71], v[82:83]
	v_pk_fma_f32 v[32:33], v[32:33], v[64:65], v[80:81]
	v_pk_fma_f32 v[30:31], v[30:31], v[62:63], v[78:79]
	v_pk_fma_f32 v[28:29], v[28:29], v[60:61], v[76:77]
	v_pk_fma_f32 v[26:27], v[26:27], v[58:59], v[74:75]
	v_pk_fma_f32 v[22:23], v[22:23], v[54:55], v[66:67]
	v_lshl_add_u64 v[66:67], v[68:69], 2, s[90:91]
	s_and_b64 vcc, exec, s[8:9]
	s_mov_b64 s[36:37], -1
	global_store_dwordx4 v[66:67], v[34:37], off
	s_cbranch_vccnz .LBB0_235
	v_mul_f32_e32 v74, v35, v35
	v_mul_f32_e32 v75, v37, v37
	v_fmac_f32_e32 v74, v34, v34
	v_fmac_f32_e32 v75, v36, v36
	v_pk_mul_f32 v[36:37], v[200:201], v[36:37]
	v_pk_mul_f32 v[34:35], v[202:203], v[34:35]
	v_add_f32_e32 v74, v74, v75
	v_cvt_pk_bf16_f32 v34, v34, v35
	v_cvt_pk_bf16_f32 v35, v36, v37
	v_lshl_add_u64 v[36:37], v[68:69], 1, s[96:97]
	global_store_dwordx2 v[36:37], v[34:35], off
	global_store_dwordx4 v[66:67], v[30:33], off offset:64
	v_mul_f32_e32 v34, v31, v31
	v_mul_f32_e32 v35, v33, v33
	v_fmac_f32_e32 v34, v30, v30
	v_fmac_f32_e32 v35, v32, v32
	v_add_f32_e32 v34, v34, v35
	v_pk_mul_f32 v[68:69], v[198:199], v[30:31]
	v_add_f32_e32 v74, v74, v34
	v_pk_mul_f32 v[34:35], v[196:197], v[32:33]
	v_cvt_pk_bf16_f32 v68, v68, v69
	v_mul_f32_e32 v75, v25, v25
	v_cvt_pk_bf16_f32 v69, v34, v35
	global_store_dwordx2 v[36:37], v[68:69], off offset:32
	global_store_dwordx4 v[66:67], v[26:29], off offset:512
	v_mul_f32_e32 v34, v27, v27
	v_mul_f32_e32 v35, v29, v29
	v_pk_mul_f32 v[68:69], v[194:195], v[26:27]
	v_fmac_f32_e32 v34, v26, v26
	v_fmac_f32_e32 v35, v28, v28
	v_cvt_pk_bf16_f32 v68, v68, v69
	v_mul_f32_e32 v69, v23, v23
	v_add_f32_e32 v34, v34, v35
	v_fmac_f32_e32 v69, v22, v22
	v_fmac_f32_e32 v75, v24, v24
	v_add_f32_e32 v74, v34, v74
	v_add_f32_e32 v69, v69, v75
	v_add_f32_e32 v74, v69, v74
	ds_bpermute_b32 v75, v226, v74
	v_pk_mul_f32 v[34:35], v[192:193], v[28:29]
	s_nop 0
	v_cvt_pk_bf16_f32 v69, v34, v35
	global_store_dwordx2 v[36:37], v[68:69], off offset:256
	global_store_dwordx4 v[66:67], v[22:25], off offset:576
	s_waitcnt lgkmcnt(0)
	v_add_f32_e32 v34, v74, v75
	ds_bpermute_b32 v35, v225, v34
	v_pk_mul_f32 v[74:75], v[186:187], v[22:23]
	v_pk_mul_f32 v[68:69], v[188:189], v[24:25]
	v_cvt_pk_bf16_f32 v74, v74, v75
	s_nop 0
	v_cvt_pk_bf16_f32 v75, v68, v69
	global_store_dwordx2 v[36:37], v[74:75], off offset:288
	s_and_saveexec_b64 s[36:37], s[6:7]
	s_cbranch_execz .LBB0_234
	s_waitcnt lgkmcnt(0)
	v_add_f32_e32 v34, v34, v35
	v_fma_f32 v34, v34, s78, 0.5
	v_trunc_f32_e32 v34, v34
	v_mul_f32_e32 v35, 0x2f800000, v34
	v_floor_f32_e32 v35, v35
	v_fmac_f32_e32 v34, 0xcf800000, v35
	v_cvt_u32_f32_e32 v34, v34
	v_cvt_u32_f32_e32 v35, v35
	v_lshl_add_u64 v[36:37], v[118:119], 3, s[14:15]
	global_atomic_add_x2 v[36:37], v[34:35], off

.LBB0_235:
	s_andn2_b64 vcc, exec, s[36:37]
	s_cbranch_vccnz .LBB0_237
	global_store_dwordx4 v[66:67], v[30:33], off offset:64
	global_store_dwordx4 v[66:67], v[26:29], off offset:512
	global_store_dwordx4 v[66:67], v[22:25], off offset:576
	s_waitcnt vmcnt(2)
.LBB0_237:
	s_nop 1
	v_lshlrev_b64 v[22:23], 10, v[98:99]
	v_lshl_add_u64 v[24:25], v[22:23], 0, v[190:191]
	s_waitcnt vmcnt(19)
	v_pk_fma_f32 v[20:21], v[20:21], v[72:73], v[52:53]
	v_pk_fma_f32 v[18:19], v[18:19], v[70:71], v[50:51]
	s_waitcnt vmcnt(18)
	v_pk_fma_f32 v[12:13], v[12:13], v[64:65], v[48:49]
	v_pk_fma_f32 v[10:11], v[10:11], v[62:63], v[46:47]
	s_waitcnt vmcnt(17)
	v_pk_fma_f32 v[8:9], v[8:9], v[60:61], v[44:45]
	v_pk_fma_f32 v[6:7], v[6:7], v[58:59], v[42:43]
	s_waitcnt vmcnt(16)
	v_pk_fma_f32 v[4:5], v[4:5], v[56:57], v[40:41]
	v_pk_fma_f32 v[2:3], v[2:3], v[54:55], v[38:39]
	v_lshl_add_u64 v[22:23], v[24:25], 2, s[90:91]
	s_and_b64 vcc, exec, s[8:9]
	s_mov_b64 s[8:9], -1
	global_store_dwordx4 v[22:23], v[18:21], off
	s_cbranch_vccnz .LBB0_242
	v_mul_f32_e32 v26, v19, v19
	v_mul_f32_e32 v27, v21, v21
	v_fmac_f32_e32 v26, v18, v18
	v_fmac_f32_e32 v27, v20, v20
	v_pk_mul_f32 v[20:21], v[200:201], v[20:21]
	v_pk_mul_f32 v[18:19], v[202:203], v[18:19]
	v_add_f32_e32 v26, v26, v27
	v_cvt_pk_bf16_f32 v18, v18, v19
	v_cvt_pk_bf16_f32 v19, v20, v21
	v_lshl_add_u64 v[20:21], v[24:25], 1, s[96:97]
	global_store_dwordx2 v[20:21], v[18:19], off
	global_store_dwordx4 v[22:23], v[10:13], off offset:64
	v_mul_f32_e32 v18, v11, v11
	v_mul_f32_e32 v19, v13, v13
	v_fmac_f32_e32 v18, v10, v10
	v_fmac_f32_e32 v19, v12, v12
	v_add_f32_e32 v18, v18, v19
	v_pk_mul_f32 v[24:25], v[198:199], v[10:11]
	v_add_f32_e32 v26, v26, v18
	v_pk_mul_f32 v[18:19], v[196:197], v[12:13]
	v_cvt_pk_bf16_f32 v24, v24, v25
	v_mul_f32_e32 v27, v5, v5
	v_cvt_pk_bf16_f32 v25, v18, v19
	global_store_dwordx2 v[20:21], v[24:25], off offset:32
	global_store_dwordx4 v[22:23], v[6:9], off offset:512
	v_mul_f32_e32 v18, v7, v7
	v_mul_f32_e32 v19, v9, v9
	v_pk_mul_f32 v[24:25], v[194:195], v[6:7]
	v_fmac_f32_e32 v18, v6, v6
	v_fmac_f32_e32 v19, v8, v8
	v_cvt_pk_bf16_f32 v24, v24, v25
	v_mul_f32_e32 v25, v3, v3
	v_add_f32_e32 v18, v18, v19
	v_fmac_f32_e32 v25, v2, v2
	v_fmac_f32_e32 v27, v4, v4
	v_add_f32_e32 v26, v18, v26
	v_add_f32_e32 v25, v25, v27
	v_add_f32_e32 v26, v25, v26
	ds_bpermute_b32 v27, v226, v26
	v_pk_mul_f32 v[18:19], v[192:193], v[8:9]
	s_nop 0
	v_cvt_pk_bf16_f32 v25, v18, v19
	global_store_dwordx2 v[20:21], v[24:25], off offset:256
	global_store_dwordx4 v[22:23], v[2:5], off offset:576
	s_waitcnt lgkmcnt(0)
	v_add_f32_e32 v18, v26, v27
	ds_bpermute_b32 v19, v225, v18
	v_pk_mul_f32 v[26:27], v[186:187], v[2:3]
	v_pk_mul_f32 v[24:25], v[188:189], v[4:5]
	v_cvt_pk_bf16_f32 v26, v26, v27
	s_nop 0
	v_cvt_pk_bf16_f32 v27, v24, v25
	global_store_dwordx2 v[20:21], v[26:27], off offset:288
	s_and_saveexec_b64 s[8:9], s[6:7]
	s_cbranch_execz .LBB0_240
	s_waitcnt lgkmcnt(0)
	v_add_f32_e32 v18, v18, v19
	v_fma_f32 v18, v18, s78, 0.5
	v_trunc_f32_e32 v18, v18
	v_mul_f32_e32 v19, 0x2f800000, v18
	v_floor_f32_e32 v19, v19
	v_fmac_f32_e32 v18, 0xcf800000, v19
	v_cvt_u32_f32_e32 v18, v18
	v_cvt_u32_f32_e32 v19, v19
	v_lshl_add_u64 v[20:21], v[98:99], 3, s[14:15]
	global_atomic_add_x2 v[20:21], v[18:19], off

.LBB0_754:
	s_mov_b32 s2, -1
	s_mov_b32 s3, s84
	s_mov_b64 s[22:23], -1
	v_mbcnt_lo_u32_b32 v70, s2, 0
	v_mbcnt_hi_u32_b32 v70, s2, v70
	v_lshl_or_b32 v154, s3, 6, v70
	s_lshl_b32 s3, s20, 8
	v_readfirstlane_b32 s2, v154
	s_ashr_i32 s6, s2, 2
	s_andn2_b32 s6, s6, 63
	s_lshr_b32 s2, s2, 1
	s_add_i32 s6, s6, s3
	s_lshl_b32 s3, s21, 8
	s_and_b32 s2, s2, 0x60
	s_or_b32 s2, s2, s3
	v_lshrrev_b32_e32 v70, 2, v154
	v_and_or_b32 v226, v70, 12, s2
	s_ashr_i32 s2, s20, 31
	s_lshr_b32 s2, s2, 28
	s_add_i32 s2, s20, s2
	s_ashr_i32 s2, s2, 4
	s_mul_i32 s20, s2, 0x6000
	s_mul_hi_i32 s7, s2, 0x6000
	s_add_u32 s2, s46, s20
	v_ashrrev_i32_e32 v227, 31, v226
	s_addc_u32 s3, s47, s7
	v_lshlrev_b64 v[220:221], 2, v[226:227]
	v_lshl_add_u64 v[70:71], s[2:3], 0, v[220:221]
	s_add_u32 s2, s48, s20
	v_and_or_b32 v234, v154, 15, s6
	v_lshl_add_u64 v[150:151], s[10:11], 0, v[220:221]
	s_addc_u32 s3, s49, s7
	v_ashrrev_i32_e32 v235, 31, v234
	v_lshl_add_u64 v[152:153], s[2:3], 0, v[220:221]
	global_load_dwordx4 v[82:85], v[70:71], off
	global_load_dwordx4 v[186:189], v[150:151], off
	global_load_dwordx4 v[202:205], v[152:153], off
	global_load_dwordx4 v[78:81], v[70:71], off offset:64
	global_load_dwordx4 v[194:197], v[150:151], off offset:64
	global_load_dwordx4 v[210:213], v[152:153], off offset:64
	global_load_dwordx4 v[74:77], v[70:71], off offset:512
	global_load_dwordx4 v[178:181], v[150:151], off offset:512
	global_load_dwordx4 v[198:201], v[152:153], off offset:512
	s_nop 0
	global_load_dwordx4 v[70:73], v[70:71], off offset:576
	s_nop 0
	global_load_dwordx4 v[190:193], v[150:151], off offset:576
	global_load_dwordx4 v[206:209], v[152:153], off offset:576
	v_lshl_add_u64 v[150:151], s[90:91], 0, v[220:221]
	v_lshlrev_b64 v[228:229], 12, v[234:235]
	v_lshl_add_u64 v[240:241], v[150:151], 0, v[228:229]
	global_load_dwordx4 v[166:169], v[240:241], off
	global_load_dwordx4 v[170:173], v[240:241], off offset:64
	global_load_dwordx4 v[230:233], v[240:241], off offset:512
	global_load_dwordx4 v[246:249], v[240:241], off offset:576
	v_or_b32_e32 v236, 16, v234
	v_ashrrev_i32_e32 v237, 31, v236
	v_lshlrev_b64 v[152:153], 12, v[236:237]
	v_lshl_add_u64 v[238:239], v[150:151], 0, v[152:153]
	v_and_b32_e32 v218, 63, v154
	global_load_dwordx4 v[162:165], v[238:239], off
	global_load_dwordx4 v[158:161], v[238:239], off offset:64
	global_load_dwordx4 v[154:157], v[238:239], off offset:512
	global_load_dwordx4 v[150:153], v[238:239], off offset:576
	v_cmp_gt_u32_e64 s[6:7], 16, v218
	s_and_b64 vcc, exec, s[14:15]
	s_waitcnt vmcnt(4)
	v_pk_fma_f32 v[182:183], v[146:147], v[82:83], v[166:167]
	v_pk_fma_f32 v[174:175], v[142:143], v[78:79], v[170:171]
	v_pk_fma_f32 v[170:171], v[138:139], v[74:75], v[230:231]
	v_or_b32_e32 v230, 32, v234
	v_ashrrev_i32_e32 v231, 31, v230
	v_pk_fma_f32 v[166:167], v[134:135], v[70:71], v[246:247]
	v_lshlrev_b64 v[134:135], 12, v[230:231]
	v_lshl_add_u64 v[134:135], s[90:91], 0, v[134:135]
	v_pk_fma_f32 v[176:177], v[144:145], v[80:81], v[172:173]
	v_pk_fma_f32 v[172:173], v[140:141], v[76:77], v[232:233]
	v_lshl_add_u64 v[232:233], v[134:135], 0, v[220:221]
	v_pk_fma_f32 v[184:185], v[148:149], v[84:85], v[168:169]
	v_pk_fma_f32 v[168:169], v[136:137], v[72:73], v[248:249]
	global_load_dwordx4 v[146:149], v[232:233], off
	global_load_dwordx4 v[142:145], v[232:233], off offset:64
	global_load_dwordx4 v[138:141], v[232:233], off offset:512
	global_load_dwordx4 v[134:137], v[232:233], off offset:576
	s_nop 0
	global_store_dwordx4 v[240:241], v[182:185], off
	s_cbranch_vccz .LBB0_756
	global_store_dwordx4 v[240:241], v[174:177], off offset:64
	global_store_dwordx4 v[240:241], v[170:173], off offset:512
	global_store_dwordx4 v[240:241], v[166:169], off offset:576
	s_waitcnt vmcnt(8)
	s_mov_b64 s[22:23], 0

.LBB0_760:
	s_waitcnt vmcnt(12)
	v_or_b32_e32 v166, 48, v234
	v_ashrrev_i32_e32 v167, 31, v166
	v_pk_fma_f32 v[150:151], v[118:119], v[70:71], v[150:151]
	v_lshlrev_b64 v[118:119], 12, v[166:167]
	v_lshl_add_u64 v[118:119], s[90:91], 0, v[118:119]
	s_waitcnt lgkmcnt(0)
	v_lshl_add_u64 v[168:169], v[226:227], 2, v[118:119]
	v_pk_fma_f32 v[164:165], v[132:133], v[84:85], v[164:165]
	v_pk_fma_f32 v[162:163], v[130:131], v[82:83], v[162:163]
	v_pk_fma_f32 v[160:161], v[128:129], v[80:81], v[160:161]
	v_pk_fma_f32 v[158:159], v[126:127], v[78:79], v[158:159]
	v_pk_fma_f32 v[156:157], v[124:125], v[76:77], v[156:157]
	v_pk_fma_f32 v[154:155], v[122:123], v[74:75], v[154:155]
	v_pk_fma_f32 v[152:153], v[120:121], v[72:73], v[152:153]
	global_load_dwordx4 v[130:133], v[168:169], off
	global_load_dwordx4 v[126:129], v[168:169], off offset:64
	global_load_dwordx4 v[122:125], v[168:169], off offset:512
	global_load_dwordx4 v[118:121], v[168:169], off offset:576
	s_mov_b64 s[22:23], -1
	s_and_b64 vcc, exec, s[14:15]
	global_store_dwordx4 v[238:239], v[162:165], off
	s_cbranch_vccz .LBB0_762
	global_store_dwordx4 v[238:239], v[158:161], off offset:64
	global_store_dwordx4 v[238:239], v[154:157], off offset:512
	global_store_dwordx4 v[238:239], v[150:153], off offset:576
	s_waitcnt vmcnt(12)
	s_mov_b64 s[22:23], 0

.LBB0_766:
	v_add_u32_e32 v150, 0x80, v234
	v_ashrrev_i32_e32 v151, 31, v150
	s_waitcnt vmcnt(20)
	v_pk_fma_f32 v[134:135], v[102:103], v[70:71], v[134:135]
	v_lshlrev_b64 v[102:103], 12, v[150:151]
	v_lshl_add_u64 v[102:103], s[90:91], 0, v[102:103]
	s_waitcnt lgkmcnt(0)
	v_lshl_add_u64 v[152:153], v[226:227], 2, v[102:103]
	v_pk_fma_f32 v[148:149], v[116:117], v[84:85], v[148:149]
	v_pk_fma_f32 v[146:147], v[114:115], v[82:83], v[146:147]
	v_pk_fma_f32 v[144:145], v[112:113], v[80:81], v[144:145]
	v_pk_fma_f32 v[142:143], v[110:111], v[78:79], v[142:143]
	v_pk_fma_f32 v[140:141], v[108:109], v[76:77], v[140:141]
	v_pk_fma_f32 v[138:139], v[106:107], v[74:75], v[138:139]
	v_pk_fma_f32 v[136:137], v[104:105], v[72:73], v[136:137]
	global_load_dwordx4 v[114:117], v[152:153], off
	global_load_dwordx4 v[110:113], v[152:153], off offset:64
	global_load_dwordx4 v[106:109], v[152:153], off offset:512
	global_load_dwordx4 v[102:105], v[152:153], off offset:576
	s_mov_b64 s[22:23], -1
	s_and_b64 vcc, exec, s[14:15]
	global_store_dwordx4 v[232:233], v[146:149], off
	s_cbranch_vccz .LBB0_768
	global_store_dwordx4 v[232:233], v[142:145], off offset:64
	global_store_dwordx4 v[232:233], v[138:141], off offset:512
	global_store_dwordx4 v[232:233], v[134:137], off offset:576
	s_waitcnt vmcnt(12)
	s_mov_b64 s[22:23], 0

.LBB0_772:
	s_waitcnt vmcnt(20)
	v_pk_fma_f32 v[118:119], v[86:87], v[70:71], v[118:119]
	v_lshl_add_u64 v[86:87], s[90:91], 0, v[228:229]
	v_lshl_add_u64 v[86:87], v[226:227], 2, v[86:87]
	s_mov_b64 s[2:3], 0x90000
	v_lshl_add_u64 v[134:135], v[86:87], 0, s[2:3]
	v_add_co_u32_e32 v86, vcc, 0x90000, v86
	v_pk_fma_f32 v[132:133], v[100:101], v[84:85], v[132:133]
	s_nop 0
	v_addc_co_u32_e32 v87, vcc, 0, v87, vcc
	v_pk_fma_f32 v[130:131], v[98:99], v[82:83], v[130:131]
	v_pk_fma_f32 v[128:129], v[96:97], v[80:81], v[128:129]
	v_pk_fma_f32 v[126:127], v[94:95], v[78:79], v[126:127]
	v_pk_fma_f32 v[124:125], v[92:93], v[76:77], v[124:125]
	v_pk_fma_f32 v[122:123], v[90:91], v[74:75], v[122:123]
	v_pk_fma_f32 v[120:121], v[88:89], v[72:73], v[120:121]
	global_load_dwordx4 v[86:89], v[86:87], off
	s_nop 0
	global_load_dwordx4 v[94:97], v[134:135], off offset:64
	global_load_dwordx4 v[90:93], v[134:135], off offset:512
	global_load_dwordx4 v[98:101], v[134:135], off offset:576
	s_mov_b64 s[22:23], -1
	s_and_b64 vcc, exec, s[14:15]
	global_store_dwordx4 v[168:169], v[130:133], off
	s_cbranch_vccz .LBB0_774
	global_store_dwordx4 v[168:169], v[126:129], off offset:64
	global_store_dwordx4 v[168:169], v[122:125], off offset:512
	global_store_dwordx4 v[168:169], v[118:121], off offset:576
	s_waitcnt vmcnt(12)
	s_mov_b64 s[22:23], 0

.LBB0_778:
	v_or_b32_e32 v118, 32, v150
	v_ashrrev_i32_e32 v119, 31, v118
	s_waitcnt vmcnt(20)
	v_pk_fma_f32 v[102:103], v[54:55], v[70:71], v[102:103]
	v_lshlrev_b64 v[54:55], 12, v[118:119]
	v_lshl_add_u64 v[54:55], s[90:91], 0, v[54:55]
	s_waitcnt lgkmcnt(0)
	v_lshl_add_u64 v[120:121], v[226:227], 2, v[54:55]
	v_pk_fma_f32 v[116:117], v[68:69], v[84:85], v[116:117]
	v_pk_fma_f32 v[114:115], v[66:67], v[82:83], v[114:115]
	v_pk_fma_f32 v[112:113], v[64:65], v[80:81], v[112:113]
	v_pk_fma_f32 v[110:111], v[62:63], v[78:79], v[110:111]
	v_pk_fma_f32 v[108:109], v[60:61], v[76:77], v[108:109]
	v_pk_fma_f32 v[106:107], v[58:59], v[74:75], v[106:107]
	v_pk_fma_f32 v[104:105], v[56:57], v[72:73], v[104:105]
	global_load_dwordx4 v[66:69], v[120:121], off
	global_load_dwordx4 v[62:65], v[120:121], off offset:64
	global_load_dwordx4 v[58:61], v[120:121], off offset:512
	global_load_dwordx4 v[54:57], v[120:121], off offset:576
	s_mov_b64 s[22:23], -1
	s_and_b64 vcc, exec, s[14:15]
	global_store_dwordx4 v[152:153], v[114:117], off
	s_cbranch_vccz .LBB0_780
	global_store_dwordx4 v[152:153], v[110:113], off offset:64
	global_store_dwordx4 v[152:153], v[106:109], off offset:512
	global_store_dwordx4 v[152:153], v[102:105], off offset:576
	s_waitcnt vmcnt(12)
	s_mov_b64 s[22:23], 0

.LBB0_784:
	s_waitcnt vmcnt(23)
	v_pk_fma_f32 v[102:103], v[50:51], v[82:83], v[86:87]
	s_waitcnt vmcnt(20)
	v_pk_fma_f32 v[86:87], v[38:39], v[70:71], v[98:99]
	v_or_b32_e32 v98, 48, v150
	v_ashrrev_i32_e32 v99, 31, v98
	v_lshlrev_b64 v[38:39], 12, v[98:99]
	v_lshl_add_u64 v[38:39], s[90:91], 0, v[38:39]
	s_waitcnt lgkmcnt(0)
	v_pk_fma_f32 v[104:105], v[52:53], v[84:85], v[88:89]
	v_pk_fma_f32 v[88:89], v[40:41], v[72:73], v[100:101]
	v_lshl_add_u64 v[100:101], v[226:227], 2, v[38:39]
	v_pk_fma_f32 v[96:97], v[48:49], v[80:81], v[96:97]
	v_pk_fma_f32 v[94:95], v[46:47], v[78:79], v[94:95]
	v_pk_fma_f32 v[92:93], v[44:45], v[76:77], v[92:93]
	v_pk_fma_f32 v[90:91], v[42:43], v[74:75], v[90:91]
	global_load_dwordx4 v[50:53], v[100:101], off
	global_load_dwordx4 v[46:49], v[100:101], off offset:64
	global_load_dwordx4 v[42:45], v[100:101], off offset:512
	global_load_dwordx4 v[38:41], v[100:101], off offset:576
	s_mov_b64 s[22:23], -1
	s_and_b64 vcc, exec, s[14:15]
	global_store_dwordx4 v[134:135], v[102:105], off
	s_cbranch_vccz .LBB0_786
	global_store_dwordx4 v[134:135], v[94:97], off offset:64
	global_store_dwordx4 v[134:135], v[90:93], off offset:512
	global_store_dwordx4 v[134:135], v[86:89], off offset:576
	s_waitcnt vmcnt(12)
	s_mov_b64 s[22:23], 0

.LBB0_790:
	s_waitcnt vmcnt(23)
	v_pk_fma_f32 v[36:37], v[36:37], v[84:85], v[68:69]
	v_pk_fma_f32 v[34:35], v[34:35], v[82:83], v[66:67]
	s_waitcnt vmcnt(22)
	v_pk_fma_f32 v[32:33], v[32:33], v[80:81], v[64:65]
	v_pk_fma_f32 v[30:31], v[30:31], v[78:79], v[62:63]
	s_waitcnt vmcnt(21)
	v_pk_fma_f32 v[28:29], v[28:29], v[76:77], v[60:61]
	v_pk_fma_f32 v[26:27], v[26:27], v[74:75], v[58:59]
	s_waitcnt vmcnt(20)
	v_pk_fma_f32 v[24:25], v[24:25], v[72:73], v[56:57]
	v_pk_fma_f32 v[22:23], v[22:23], v[70:71], v[54:55]
	s_mov_b64 s[22:23], -1
	s_and_b64 vcc, exec, s[14:15]
	global_store_dwordx4 v[120:121], v[34:37], off
	s_cbranch_vccz .LBB0_792
	global_store_dwordx4 v[120:121], v[30:33], off offset:64
	global_store_dwordx4 v[120:121], v[26:29], off offset:512
	global_store_dwordx4 v[120:121], v[22:25], off offset:576
	s_waitcnt vmcnt(8)
	s_mov_b64 s[22:23], 0

.LBB0_796:
	s_waitcnt vmcnt(19)
	v_pk_fma_f32 v[20:21], v[20:21], v[84:85], v[52:53]
	v_pk_fma_f32 v[18:19], v[18:19], v[82:83], v[50:51]
	s_waitcnt vmcnt(18)
	v_pk_fma_f32 v[12:13], v[12:13], v[80:81], v[48:49]
	v_pk_fma_f32 v[10:11], v[10:11], v[78:79], v[46:47]
	s_waitcnt vmcnt(17)
	v_pk_fma_f32 v[8:9], v[8:9], v[76:77], v[44:45]
	v_pk_fma_f32 v[6:7], v[6:7], v[74:75], v[42:43]
	s_waitcnt vmcnt(16)
	v_pk_fma_f32 v[4:5], v[4:5], v[72:73], v[40:41]
	v_pk_fma_f32 v[2:3], v[2:3], v[70:71], v[38:39]
	s_mov_b64 s[22:23], -1
	s_and_b64 vcc, exec, s[14:15]
	global_store_dwordx4 v[100:101], v[18:21], off
	s_cbranch_vccz .LBB0_799
	global_store_dwordx4 v[100:101], v[10:13], off offset:64
	global_store_dwordx4 v[100:101], v[6:9], off offset:512
	global_store_dwordx4 v[100:101], v[2:5], off offset:576
	s_cbranch_execz .LBB0_800
